# v8_p0_stores_writethrough_no_wbl2
# speedup vs baseline: 1.0517x; 1.0019x over previous
.LBB0_14:
	v_add_u32_e32 v32, s35, v60
	v_ashrrev_i32_e32 v33, 31, v32
	v_lshl_add_u64 v[34:35], v[32:33], 2, v[56:57]
	v_lshlrev_b64 v[32:33], 11, v[32:33]
	global_load_dwordx4 v[44:47], v[34:35], off nt
	global_load_dwordx4 v[40:43], v[34:35], off offset:16 nt
	v_lshl_add_u64 v[62:63], v[34:35], 0, s[0:1]
	v_add_co_u32_e32 v34, vcc, s26, v34
	v_lshl_add_u64 v[64:65], v[54:55], 0, v[32:33]
	s_nop 0
	v_addc_co_u32_e32 v35, vcc, 0, v35, vcc
	global_load_dwordx4 v[36:39], v[34:35], off nt
	s_nop 0
	global_load_dwordx4 v[32:35], v[62:63], off offset:16 nt
	global_load_dword v50, v[64:65], off nt
	global_load_dword v68, v[64:65], off offset:2048 nt
	global_load_dword v69, v[64:65], off offset:64 nt
	global_load_dword v70, v[64:65], off offset:2112 nt
	global_load_dword v71, v[64:65], off offset:128 nt
	global_load_dword v72, v[64:65], off offset:2176 nt
	global_load_dword v73, v[64:65], off offset:2240 nt
	global_load_dword v74, v[64:65], off offset:192 nt
	v_add_co_u32_e32 v62, vcc, s27, v64
	s_add_i32 s35, s35, 32
	s_nop 0
	v_addc_co_u32_e32 v63, vcc, 0, v65, vcc
	v_add_co_u32_e32 v66, vcc, s28, v64
	s_cmpk_lg_i32 s35, 0x80
	s_nop 0
	v_addc_co_u32_e32 v67, vcc, 0, v65, vcc
	v_add_co_u32_e32 v64, vcc, s29, v64
	s_waitcnt vmcnt(11)
	v_bfe_u32 v94, v45, 16, 1
	v_addc_co_u32_e32 v65, vcc, 0, v65, vcc
	global_load_dword v75, v[64:65], off nt
	global_load_dword v76, v[64:65], off offset:2048 nt
	global_load_dword v77, v[64:65], off offset:64 nt
	global_load_dword v78, v[64:65], off offset:2112 nt
	global_load_dword v79, v[64:65], off offset:128 nt
	global_load_dword v80, v[64:65], off offset:2176 nt
	global_load_dword v81, v[64:65], off offset:2240 nt
	global_load_dword v82, v[66:67], off offset:-4096 nt
	s_nop 0
	global_load_dword v64, v[64:65], off offset:192 nt
	s_nop 0
	global_load_dword v65, v[62:63], off offset:2048 nt
	global_load_dword v83, v[66:67], off nt
	global_load_dword v84, v[66:67], off offset:2048 nt
	global_load_dword v85, v[62:63], off offset:2112 nt
	global_load_dword v86, v[62:63], off offset:64 nt
	global_load_dword v87, v[66:67], off offset:64 nt
	global_load_dword v88, v[66:67], off offset:2112 nt
	global_load_dword v89, v[62:63], off offset:2176 nt
	global_load_dword v90, v[62:63], off offset:128 nt
	global_load_dword v91, v[66:67], off offset:128 nt
	global_load_dword v92, v[66:67], off offset:2176 nt
	global_load_dword v93, v[62:63], off offset:2240 nt
	s_nop 0
	global_load_dword v62, v[62:63], off offset:192 nt
	s_nop 0
	global_load_dword v63, v[66:67], off offset:2240 nt
	s_nop 0
	global_load_dword v66, v[66:67], off offset:192 nt
	v_bfe_u32 v67, v44, 16, 1
	v_bfe_u32 v95, v46, 16, 1
	v_bfe_u32 v97, v47, 16, 1
	s_waitcnt vmcnt(34)
	v_bfe_u32 v98, v40, 16, 1
	v_bfe_u32 v100, v41, 16, 1
	v_bfe_u32 v101, v42, 16, 1
	v_bfe_u32 v102, v43, 16, 1
	v_add3_u32 v44, v44, v67, s24
	v_add3_u32 v45, v45, v94, s24
	v_add3_u32 v46, v46, v95, s24
	v_add3_u32 v47, v47, v97, s24
	v_add3_u32 v40, v40, v98, s24
	v_add3_u32 v41, v41, v100, s24
	v_add3_u32 v42, v42, v101, s24
	v_add3_u32 v43, v43, v102, s24
	s_waitcnt vmcnt(33)
	v_bfe_u32 v67, v36, 16, 1
	v_bfe_u32 v94, v37, 16, 1
	v_bfe_u32 v95, v38, 16, 1
	v_bfe_u32 v97, v39, 16, 1
	s_waitcnt vmcnt(32)
	v_bfe_u32 v98, v32, 16, 1
	v_bfe_u32 v100, v33, 16, 1
	v_bfe_u32 v101, v34, 16, 1
	v_bfe_u32 v102, v35, 16, 1
	s_waitcnt vmcnt(31)
	v_bfe_u32 v103, v50, 16, 1
	s_waitcnt vmcnt(30)
	v_bfe_u32 v104, v68, 16, 1
	s_waitcnt vmcnt(29)
	v_bfe_u32 v105, v69, 16, 1
	s_waitcnt vmcnt(28)
	v_bfe_u32 v106, v70, 16, 1
	s_waitcnt vmcnt(27)
	v_bfe_u32 v107, v71, 16, 1
	s_waitcnt vmcnt(26)
	v_bfe_u32 v108, v72, 16, 1
	s_waitcnt vmcnt(24)
	v_bfe_u32 v109, v74, 16, 1
	v_bfe_u32 v110, v73, 16, 1
	v_add3_u32 v36, v36, v67, s24
	v_add3_u32 v94, v37, v94, s24
	v_add3_u32 v38, v38, v95, s24
	v_add3_u32 v95, v39, v97, s24
	v_add3_u32 v39, v32, v98, s24
	v_add3_u32 v97, v33, v100, s24
	v_add3_u32 v37, v34, v101, s24
	v_add3_u32 v67, v35, v102, s24
	v_lshrrev_b32_e32 v32, 16, v44
	v_perm_b32 v35, v43, v42, s30
	v_lshrrev_b32_e32 v33, 16, v46
	v_lshrrev_b32_e32 v34, 16, v40
	v_add3_u32 v40, v50, v103, s24
	v_add3_u32 v42, v68, v104, s24
	v_add3_u32 v46, v69, v105, s24
	v_add3_u32 v50, v70, v106, s24
	v_add3_u32 v70, v71, v107, s24
	v_add3_u32 v71, v72, v108, s24
	v_add3_u32 v74, v74, v109, s24
	v_add3_u32 v73, v73, v110, s24
	v_and_or_b32 v32, v45, s25, v32
	v_and_or_b32 v33, v47, s25, v33
	v_and_or_b32 v34, v41, s25, v34
	v_lshrrev_b32_e32 v40, 16, v40
	v_lshrrev_b32_e32 v46, 16, v46
	s_waitcnt vmcnt(23)
	v_bfe_u32 v43, v75, 16, 1
	s_waitcnt vmcnt(22)
	v_bfe_u32 v44, v76, 16, 1
	s_waitcnt vmcnt(21)
	v_bfe_u32 v68, v77, 16, 1
	s_waitcnt vmcnt(20)
	v_bfe_u32 v69, v78, 16, 1
	s_waitcnt vmcnt(19)
	v_bfe_u32 v72, v79, 16, 1
	s_waitcnt vmcnt(18)
	v_bfe_u32 v98, v80, 16, 1
	s_waitcnt vmcnt(17)
	v_bfe_u32 v101, v81, 16, 1
	s_waitcnt vmcnt(16)
	v_bfe_u32 v102, v82, 16, 1
	s_waitcnt vmcnt(15)
	v_bfe_u32 v100, v64, 16, 1
	s_waitcnt vmcnt(14)
	v_bfe_u32 v103, v65, 16, 1
	s_waitcnt vmcnt(13)
	v_bfe_u32 v104, v83, 16, 1
	s_waitcnt vmcnt(12)
	v_bfe_u32 v105, v84, 16, 1
	s_waitcnt vmcnt(11)
	v_bfe_u32 v107, v85, 16, 1
	s_waitcnt vmcnt(10)
	v_bfe_u32 v106, v86, 16, 1
	s_waitcnt vmcnt(9)
	v_bfe_u32 v108, v87, 16, 1
	s_waitcnt vmcnt(8)
	v_bfe_u32 v109, v88, 16, 1
	s_waitcnt vmcnt(7)
	v_bfe_u32 v111, v89, 16, 1
	s_waitcnt vmcnt(6)
	v_bfe_u32 v110, v90, 16, 1
	s_waitcnt vmcnt(5)
	v_bfe_u32 v112, v91, 16, 1
	s_waitcnt vmcnt(4)
	v_bfe_u32 v113, v92, 16, 1
	s_waitcnt vmcnt(3)
	v_bfe_u32 v115, v93, 16, 1
	s_waitcnt vmcnt(2)
	v_bfe_u32 v114, v62, 16, 1
	s_waitcnt vmcnt(1)
	v_bfe_u32 v117, v63, 16, 1
	s_waitcnt vmcnt(0)
	v_bfe_u32 v116, v66, 16, 1
	v_add3_u32 v41, v75, v43, s24
	v_add3_u32 v43, v76, v44, s24
	v_add3_u32 v44, v77, v68, s24
	v_add3_u32 v45, v78, v69, s24
	v_add3_u32 v47, v79, v72, s24
	v_add3_u32 v68, v80, v98, s24
	v_lshrrev_b32_e32 v69, 16, v70
	v_add3_u32 v70, v81, v101, s24
	v_lshrrev_b32_e32 v72, 16, v74
	v_add3_u32 v74, v82, v102, s24
	v_add3_u32 v76, v83, v104, s24
	v_add3_u32 v77, v84, v105, s24
	v_add3_u32 v78, v86, v106, s24
	v_add3_u32 v80, v87, v108, s24
	v_add3_u32 v81, v88, v109, s24
	v_add3_u32 v82, v90, v110, s24
	v_add3_u32 v84, v91, v112, s24
	v_add3_u32 v86, v62, v114, s24
	v_add3_u32 v88, v66, v116, s24
	v_add3_u32 v64, v64, v100, s24
	v_add3_u32 v75, v65, v103, s24
	v_add3_u32 v79, v85, v107, s24
	v_add3_u32 v83, v89, v111, s24
	v_add3_u32 v85, v92, v113, s24
	v_add3_u32 v87, v93, v115, s24
	v_add3_u32 v89, v63, v117, s24
	v_lshrrev_b32_e32 v90, 16, v38
	v_lshrrev_b32_e32 v91, 16, v39
	v_and_or_b32 v38, v42, s25, v40
	v_perm_b32 v41, v43, v41, s30
	v_and_or_b32 v42, v50, s25, v46
	v_perm_b32 v45, v45, v44, s30
	v_perm_b32 v65, v68, v47, s30
	v_lshrrev_b32_e32 v39, 16, v74
	v_lshrrev_b32_e32 v40, 16, v76
	v_lshrrev_b32_e32 v43, 16, v78
	v_lshrrev_b32_e32 v44, 16, v80
	v_lshrrev_b32_e32 v46, 16, v82
	v_lshrrev_b32_e32 v47, 16, v84
	v_lshrrev_b32_e32 v50, 16, v86
	v_lshrrev_b32_e32 v68, 16, v88
	v_perm_b32 v37, v67, v37, s30
	v_and_or_b32 v62, v71, s25, v69
	v_and_or_b32 v66, v73, s25, v72
	v_perm_b32 v69, v70, v64, s30
	v_and_or_b32 v39, v75, s25, v39
	v_and_or_b32 v40, v77, s25, v40
	v_and_or_b32 v43, v79, s25, v43
	v_and_or_b32 v44, v81, s25, v44
	v_and_or_b32 v63, v83, s25, v46
	v_and_or_b32 v64, v85, s25, v47
	v_and_or_b32 v67, v87, s25, v50
	v_and_or_b32 v68, v89, s25, v68
	v_lshrrev_b32_e32 v36, 16, v36
	v_mfma_f32_16x16x32_bf16 v[28:31], v[38:41], v[32:35], v[28:31]
	v_mfma_f32_16x16x32_bf16 v[24:27], v[42:45], v[32:35], v[24:27]
	v_mfma_f32_16x16x32_bf16 v[20:23], v[62:65], v[32:35], v[20:23]
	v_mfma_f32_16x16x32_bf16 v[16:19], v[66:69], v[32:35], v[16:19]
	v_and_or_b32 v34, v94, s25, v36
	v_and_or_b32 v35, v95, s25, v90
	v_and_or_b32 v36, v97, s25, v91
	s_nop 1
	v_mfma_f32_16x16x32_bf16 v[12:15], v[38:41], v[34:37], v[12:15]
	v_mfma_f32_16x16x32_bf16 v[8:11], v[42:45], v[34:37], v[8:11]
	v_mfma_f32_16x16x32_bf16 v[4:7], v[62:65], v[34:37], v[4:7]
	v_mfma_f32_16x16x32_bf16 v[0:3], v[66:69], v[34:37], v[0:3]
	s_cbranch_scc1 .LBB0_14
	ds_write_b128 v61, v[28:31]
	ds_write_b128 v61, v[24:27] offset:1024
	ds_write_b128 v61, v[20:23] offset:2048
	ds_write_b128 v61, v[16:19] offset:3072
	ds_write_b128 v61, v[12:15] offset:4096
	ds_write_b128 v61, v[8:11] offset:5120
	ds_write_b128 v61, v[4:7] offset:6144
	ds_write_b128 v61, v[0:3] offset:7168
	s_waitcnt lgkmcnt(0)
	s_barrier
	ds_read_b128 v[0:3], v49
	ds_read_b128 v[4:7], v49 offset:8192
	ds_read_b128 v[8:11], v49 offset:16384
	s_lshl_b64 s[20:21], s[20:21], 19
	s_add_u32 s20, s22, s20
	s_waitcnt lgkmcnt(2)
	v_pk_add_f32 v[2:3], v[2:3], 0 op_sel_hi:[1,0]
	v_pk_add_f32 v[12:13], v[0:1], 0 op_sel_hi:[1,0]
	s_waitcnt lgkmcnt(1)
	v_pk_add_f32 v[6:7], v[2:3], v[6:7]
	ds_read_b128 v[0:3], v49 offset:24576
	v_pk_add_f32 v[12:13], v[12:13], v[4:5]
	s_waitcnt lgkmcnt(1)
	v_pk_add_f32 v[10:11], v[6:7], v[10:11]
	ds_read_b128 v[4:7], v49 offset:32768
	v_pk_add_f32 v[8:9], v[12:13], v[8:9]
	s_waitcnt lgkmcnt(1)
	v_pk_add_f32 v[10:11], v[10:11], v[2:3]
	v_pk_add_f32 v[12:13], v[8:9], v[0:1]
	ds_read_b128 v[0:3], v49 offset:40960
	s_waitcnt lgkmcnt(1)
	v_pk_add_f32 v[14:15], v[10:11], v[6:7]
	ds_read_b128 v[6:9], v49 offset:49152
	v_pk_add_f32 v[4:5], v[12:13], v[4:5]
	ds_read_b128 v[10:13], v49 offset:57344
	s_waitcnt lgkmcnt(2)
	v_pk_add_f32 v[0:1], v[4:5], v[0:1]
	v_add_u32_e32 v4, s34, v58
	s_addc_u32 s21, s23, s21
	s_lshl_b32 s34, s31, 16
	s_and_b32 s34, s34, 0x40000
	s_add_u32 s20, s20, s34
	v_ashrrev_i32_e32 v5, 31, v4
	s_addc_u32 s21, s21, 0
	v_lshlrev_b64 v[4:5], 9, v[4:5]
	s_waitcnt lgkmcnt(1)
	v_pk_add_f32 v[0:1], v[0:1], v[6:7]
	v_lshl_add_u64 v[4:5], s[20:21], 0, v[4:5]
	s_and_b32 s20, s33, 0xc0
	s_waitcnt lgkmcnt(0)
	v_pk_add_f32 v[0:1], v[0:1], v[10:11]
	v_or_b32_e32 v6, s20, v59
	v_pk_add_f32 v[2:3], v[14:15], v[2:3]
	v_lshlrev_b32_e32 v50, 1, v6
	v_bfe_u32 v6, v0, 16, 1
	v_pk_add_f32 v[2:3], v[2:3], v[8:9]
	v_add3_u32 v0, v0, v6, s24
	v_bfe_u32 v6, v1, 16, 1
	v_pk_add_f32 v[2:3], v[2:3], v[12:13]
	v_lshrrev_b32_e32 v0, 16, v0
	v_add3_u32 v1, v1, v6, s24
	v_and_or_b32 v0, v1, s25, v0
	v_bfe_u32 v1, v2, 16, 1
	v_add3_u32 v1, v2, v1, s24
	v_bfe_u32 v2, v3, 16, 1
	v_lshrrev_b32_e32 v1, 16, v1
	v_add3_u32 v2, v3, v2, s24
	s_add_i32 s31, s31, s68
	v_lshl_add_u64 v[4:5], v[4:5], 0, v[50:51]
	v_and_or_b32 v1, v2, s25, v1
	s_cmpk_gt_i32 s31, 0xff
	global_store_dwordx2 v[4:5], v[0:1], off sc1
	s_barrier
	s_cbranch_scc0 .LBB0_13

.LBB0_87:
	v_mad_i64_i32 v[6:7], s[0:1], s57, v98, 0
	v_lshl_add_u64 v[6:7], v[6:7], 1, s[20:21]
	s_ashr_i32 s23, s22, 31
	v_lshl_add_u64 v[6:7], s[22:23], 1, v[6:7]
	v_lshlrev_b32_e32 v0, 1, v100
	v_lshl_add_u64 v[6:7], v[6:7], 0, v[0:1]
	global_store_dwordx4 v[6:7], v[2:5], off sc1
	s_andn2_b64 vcc, exec, s[40:41]
	s_mov_b64 s[24:25], -1
	v_cndmask_b32_e64 v2, 0, 1, s[40:41]
	v_cmp_ne_u32_e64 s[0:1], 1, v2
	s_cbranch_vccnz .LBB0_89
	ds_read2_b32 v[2:3], v101 offset0:8 offset1:41
	ds_read2_b32 v[4:5], v101 offset0:74 offset1:107
	s_mov_b64 s[24:25], 0
	s_waitcnt lgkmcnt(1)
	v_bfe_u32 v6, v2, 16, 1
	v_bfe_u32 v7, v3, 16, 1
	v_add3_u32 v2, v2, v6, s66
	v_add3_u32 v3, v3, v7, s66
	ds_read2_b32 v[6:7], v101 offset0:140 offset1:173
	s_waitcnt lgkmcnt(1)
	v_bfe_u32 v8, v4, 16, 1
	v_lshrrev_b32_e32 v2, 16, v2
	v_and_or_b32 v2, v3, s67, v2
	v_add3_u32 v3, v4, v8, s66
	v_bfe_u32 v4, v5, 16, 1
	ds_read2_b32 v[8:9], v101 offset0:206 offset1:239
	v_lshrrev_b32_e32 v3, 16, v3
	v_add3_u32 v4, v5, v4, s66
	v_and_or_b32 v3, v4, s67, v3
	s_waitcnt lgkmcnt(1)
	v_bfe_u32 v4, v6, 16, 1
	v_add3_u32 v4, v6, v4, s66
	v_bfe_u32 v5, v7, 16, 1
	v_lshrrev_b32_e32 v4, 16, v4
	v_add3_u32 v5, v7, v5, s66
	v_and_or_b32 v4, v5, s67, v4
	s_waitcnt lgkmcnt(0)
	v_bfe_u32 v5, v8, 16, 1
	v_add3_u32 v5, v8, v5, s66
	v_bfe_u32 v6, v9, 16, 1
	v_lshrrev_b32_e32 v5, 16, v5
	v_add3_u32 v6, v9, v6, s66
	v_and_or_b32 v5, v6, s67, v5

.LBB0_91:
	v_mad_i64_i32 v[6:7], s[24:25], s57, v102, 0
	v_lshl_add_u64 v[6:7], v[6:7], 1, s[20:21]
	v_lshl_add_u64 v[6:7], s[22:23], 1, v[6:7]
	v_lshl_add_u64 v[6:7], v[6:7], 0, v[0:1]
	s_and_b64 vcc, exec, s[0:1]
	s_mov_b64 s[24:25], -1
	global_store_dwordx4 v[6:7], v[2:5], off sc1
	s_cbranch_vccnz .LBB0_93
	ds_read2_b32 v[2:3], v101 offset0:16 offset1:49
	ds_read2_b32 v[4:5], v101 offset0:82 offset1:115
	s_mov_b64 s[24:25], 0
	s_waitcnt lgkmcnt(1)
	v_bfe_u32 v6, v2, 16, 1
	v_bfe_u32 v7, v3, 16, 1
	v_add3_u32 v2, v2, v6, s66
	v_add3_u32 v3, v3, v7, s66
	ds_read2_b32 v[6:7], v101 offset0:148 offset1:181
	s_waitcnt lgkmcnt(1)
	v_bfe_u32 v8, v4, 16, 1
	v_lshrrev_b32_e32 v2, 16, v2
	v_and_or_b32 v2, v3, s67, v2
	v_add3_u32 v3, v4, v8, s66
	v_bfe_u32 v4, v5, 16, 1
	ds_read2_b32 v[8:9], v101 offset0:214 offset1:247
	v_lshrrev_b32_e32 v3, 16, v3
	v_add3_u32 v4, v5, v4, s66
	v_and_or_b32 v3, v4, s67, v3
	s_waitcnt lgkmcnt(1)
	v_bfe_u32 v4, v6, 16, 1
	v_add3_u32 v4, v6, v4, s66
	v_bfe_u32 v5, v7, 16, 1
	v_lshrrev_b32_e32 v4, 16, v4
	v_add3_u32 v5, v7, v5, s66
	v_and_or_b32 v4, v5, s67, v4
	s_waitcnt lgkmcnt(0)
	v_bfe_u32 v5, v8, 16, 1
	v_add3_u32 v5, v8, v5, s66
	v_bfe_u32 v6, v9, 16, 1
	v_lshrrev_b32_e32 v5, 16, v5
	v_add3_u32 v6, v9, v6, s66
	v_and_or_b32 v5, v6, s67, v5

.LBB0_95:
	v_mad_i64_i32 v[6:7], s[24:25], s57, v104, 0
	v_lshl_add_u64 v[6:7], v[6:7], 1, s[20:21]
	v_lshl_add_u64 v[6:7], s[22:23], 1, v[6:7]
	v_lshl_add_u64 v[6:7], v[6:7], 0, v[0:1]
	s_and_b64 vcc, exec, s[0:1]
	s_mov_b64 s[0:1], -1
	global_store_dwordx4 v[6:7], v[2:5], off sc1
	s_cbranch_vccnz .LBB0_97
	ds_read2_b32 v[2:3], v101 offset0:24 offset1:57
	ds_read2_b32 v[4:5], v101 offset0:90 offset1:123
	s_mov_b64 s[0:1], 0
	s_waitcnt lgkmcnt(1)
	v_bfe_u32 v6, v2, 16, 1
	v_bfe_u32 v7, v3, 16, 1
	v_add3_u32 v2, v2, v6, s66
	v_add3_u32 v3, v3, v7, s66
	ds_read2_b32 v[6:7], v101 offset0:156 offset1:189
	s_waitcnt lgkmcnt(1)
	v_bfe_u32 v8, v4, 16, 1
	v_lshrrev_b32_e32 v2, 16, v2
	v_and_or_b32 v2, v3, s67, v2
	v_add3_u32 v3, v4, v8, s66
	v_bfe_u32 v4, v5, 16, 1
	ds_read2_b32 v[8:9], v101 offset0:222 offset1:255
	v_lshrrev_b32_e32 v3, 16, v3
	v_add3_u32 v4, v5, v4, s66
	v_and_or_b32 v3, v4, s67, v3
	s_waitcnt lgkmcnt(1)
	v_bfe_u32 v4, v6, 16, 1
	v_add3_u32 v4, v6, v4, s66
	v_bfe_u32 v5, v7, 16, 1
	v_lshrrev_b32_e32 v4, 16, v4
	v_add3_u32 v5, v7, v5, s66
	v_and_or_b32 v4, v5, s67, v4
	s_waitcnt lgkmcnt(0)
	v_bfe_u32 v5, v8, 16, 1
	v_add3_u32 v5, v8, v5, s66
	v_bfe_u32 v6, v9, 16, 1
	v_lshrrev_b32_e32 v5, 16, v5
	v_add3_u32 v6, v9, v6, s66
	v_and_or_b32 v5, v6, s67, v5

.LBB0_99:
	v_mad_i64_i32 v[6:7], s[0:1], s57, v106, 0
	v_lshl_add_u64 v[6:7], v[6:7], 1, s[20:21]
	v_lshl_add_u64 v[6:7], s[22:23], 1, v[6:7]
	v_lshl_add_u64 v[6:7], v[6:7], 0, v[0:1]
	global_store_dwordx4 v[6:7], v[2:5], off sc1
	s_waitcnt lgkmcnt(0)
	s_branch .LBB0_55
.LBB0_100:
	v_mad_i64_i32 v[2:3], s[0:1], s57, v98, 0
	s_ashr_i32 s23, s22, 31
	v_lshl_add_u64 v[2:3], v[2:3], 1, s[20:21]
	s_lshl_b64 s[0:1], s[22:23], 1
	s_mov_b32 s24, s29
	s_mov_b32 s25, s29
	v_lshl_add_u64 v[2:3], v[2:3], 0, s[0:1]
	v_lshlrev_b32_e32 v0, 1, v100
	s_mov_b32 s26, s29
	s_mov_b32 s27, s29
	v_mov_b64_e32 v[4:5], s[24:25]
	v_lshl_add_u64 v[2:3], v[2:3], 0, v[0:1]
	v_mov_b64_e32 v[6:7], s[26:27]
	global_store_dwordx4 v[2:3], v[4:7], off sc1
	v_mad_i64_i32 v[2:3], s[22:23], s57, v102, 0
	v_lshl_add_u64 v[2:3], v[2:3], 1, s[20:21]
	v_lshl_add_u64 v[2:3], v[2:3], 0, s[0:1]
	v_lshl_add_u64 v[2:3], v[2:3], 0, v[0:1]
	global_store_dwordx4 v[2:3], v[4:7], off sc1
	v_mad_i64_i32 v[2:3], s[22:23], s57, v104, 0
	v_lshl_add_u64 v[2:3], v[2:3], 1, s[20:21]
	v_lshl_add_u64 v[2:3], v[2:3], 0, s[0:1]
	v_lshl_add_u64 v[2:3], v[2:3], 0, v[0:1]
	global_store_dwordx4 v[2:3], v[4:7], off sc1
	v_mad_i64_i32 v[2:3], s[22:23], s57, v106, 0
	v_lshl_add_u64 v[2:3], v[2:3], 1, s[20:21]
	v_lshl_add_u64 v[2:3], v[2:3], 0, s[0:1]
	v_lshl_add_u64 v[2:3], v[2:3], 0, v[0:1]
	global_store_dwordx4 v[2:3], v[4:7], off sc1
	s_branch .LBB0_55

.LBB0_113:
	s_mul_i32 s0, s68, 48
	s_lshl_b32 s1, s56, 2
	s_add_i32 s0, s1, s0
	s_ashr_i32 s1, s0, 31
	s_lshl_b64 s[10:11], s[0:1], 12
	s_add_u32 s10, s4, s10
	v_ashrrev_i32_e32 v97, 31, v96
	s_addc_u32 s11, s5, s11
	s_waitcnt vmcnt(30)
	v_lshlrev_b64 v[32:33], 4, v[96:97]
	v_lshl_add_u64 v[16:17], s[10:11], 0, v[32:33]
	s_or_b32 s10, s0, 2
	s_ashr_i32 s11, s10, 31
	s_lshl_b64 s[12:13], s[10:11], 12
	s_add_u32 s12, s4, s12
	v_add_co_u32_e32 v28, vcc, 0x1000, v16
	s_addc_u32 s13, s5, s13
	global_load_dwordx4 v[0:3], v[16:17], off nt
	global_load_dwordx4 v[4:7], v[16:17], off offset:1024 nt
	global_load_dwordx4 v[8:11], v[16:17], off offset:2048 nt
	global_load_dwordx4 v[12:15], v[16:17], off offset:3072 nt
	v_addc_co_u32_e32 v29, vcc, 0, v17, vcc
	s_movk_i32 s14, 0x1000
	s_waitcnt vmcnt(18)
	v_lshl_add_u64 v[48:49], s[12:13], 0, v[32:33]
	global_load_dwordx4 v[16:19], v[28:29], off nt
	global_load_dwordx4 v[20:23], v[28:29], off offset:1024 nt
	global_load_dwordx4 v[24:27], v[28:29], off offset:2048 nt
	v_add_co_u32_e32 v64, vcc, s14, v48
	global_load_dwordx4 v[28:31], v[28:29], off offset:3072 nt
	s_nop 0
	v_addc_co_u32_e32 v65, vcc, 0, v49, vcc
	global_load_dwordx4 v[32:35], v[48:49], off nt
	global_load_dwordx4 v[36:39], v[48:49], off offset:1024 nt
	global_load_dwordx4 v[40:43], v[48:49], off offset:2048 nt
	global_load_dwordx4 v[44:47], v[48:49], off offset:3072 nt
	s_nop 0
	global_load_dwordx4 v[48:51], v[64:65], off nt
	global_load_dwordx4 v[52:55], v[64:65], off offset:1024 nt
	global_load_dwordx4 v[56:59], v[64:65], off offset:2048 nt
	global_load_dwordx4 v[60:63], v[64:65], off offset:3072 nt
	s_lshl_b64 s[0:1], s[0:1], 11
	s_add_u32 s0, s6, s0
	v_lshlrev_b64 v[64:65], 3, v[96:97]
	s_addc_u32 s1, s7, s1
	s_lshl_b64 s[10:11], s[10:11], 11
	v_lshl_add_u64 v[66:67], s[0:1], 0, v[64:65]
	s_add_u32 s0, s6, s10
	s_addc_u32 s1, s7, s11
	v_lshl_add_u64 v[64:65], s[0:1], 0, v[64:65]
	v_readlane_b32 s88, v246, 36
	s_mov_b64 s[0:1], 0
	v_readlane_b32 s89, v246, 37
	s_waitcnt vmcnt(15)
	v_cvt_pk_f16_f32 v0, v0, v1
	v_cvt_pk_f16_f32 v1, v2, v3
	s_waitcnt vmcnt(14)
	v_cvt_pk_f16_f32 v2, v4, v5
	v_cvt_pk_f16_f32 v3, v6, v7
	s_waitcnt vmcnt(13)
	v_cvt_pk_f16_f32 v4, v8, v9
	v_cvt_pk_f16_f32 v5, v10, v11
	s_waitcnt vmcnt(12)
	v_cvt_pk_f16_f32 v6, v12, v13
	v_cvt_pk_f16_f32 v7, v14, v15
	global_store_dwordx2 v[66:67], v[0:1], off sc1
	global_store_dwordx2 v[66:67], v[2:3], off offset:512 sc1
	global_store_dwordx2 v[66:67], v[4:5], off offset:1024 sc1
	global_store_dwordx2 v[66:67], v[6:7], off offset:1536 sc1
	s_waitcnt vmcnt(15)
	v_cvt_pk_f16_f32 v0, v16, v17
	v_cvt_pk_f16_f32 v1, v18, v19
	s_waitcnt vmcnt(14)
	v_cvt_pk_f16_f32 v2, v20, v21
	v_cvt_pk_f16_f32 v3, v22, v23
	s_waitcnt vmcnt(13)
	v_cvt_pk_f16_f32 v4, v24, v25
	v_cvt_pk_f16_f32 v5, v26, v27
	s_waitcnt vmcnt(12)
	v_cvt_pk_f16_f32 v6, v28, v29
	v_cvt_pk_f16_f32 v7, v30, v31
	global_store_dwordx2 v[66:67], v[0:1], off offset:2048 sc1
	global_store_dwordx2 v[66:67], v[2:3], off offset:2560 sc1
	global_store_dwordx2 v[66:67], v[4:5], off offset:3072 sc1
	global_store_dwordx2 v[66:67], v[6:7], off offset:3584 sc1
	s_waitcnt vmcnt(15)
	v_cvt_pk_f16_f32 v0, v32, v33
	v_cvt_pk_f16_f32 v1, v34, v35
	s_waitcnt vmcnt(14)
	v_cvt_pk_f16_f32 v2, v36, v37
	v_cvt_pk_f16_f32 v3, v38, v39
	s_waitcnt vmcnt(13)
	v_cvt_pk_f16_f32 v4, v40, v41
	v_cvt_pk_f16_f32 v5, v42, v43
	global_store_dwordx2 v[64:65], v[0:1], off sc1
	s_waitcnt vmcnt(12)
	v_cvt_pk_f16_f32 v0, v48, v49
	v_cvt_pk_f16_f32 v1, v50, v51
	v_cvt_pk_f16_f32 v6, v44, v45
	global_store_dwordx2 v[64:65], v[2:3], off offset:512 sc1
	s_waitcnt vmcnt(12)
	v_cvt_pk_f16_f32 v2, v52, v53
	v_cvt_pk_f16_f32 v3, v54, v55
	global_store_dwordx2 v[64:65], v[4:5], off offset:1024 sc1
	s_waitcnt vmcnt(12)
	v_cvt_pk_f16_f32 v4, v56, v57
	v_cvt_pk_f16_f32 v5, v58, v59
	global_store_dwordx2 v[64:65], v[0:1], off offset:2048 sc1
	global_store_dwordx2 v[64:65], v[2:3], off offset:2560 sc1
	global_store_dwordx2 v[64:65], v[4:5], off offset:3072 sc1
	v_cvt_pk_f16_f32 v7, v46, v47
	s_waitcnt vmcnt(14)
	v_cvt_pk_f16_f32 v0, v60, v61
	v_cvt_pk_f16_f32 v1, v62, v63
	global_store_dwordx2 v[64:65], v[6:7], off offset:1536 sc1
	global_store_dwordx2 v[64:65], v[0:1], off offset:3584 sc1

.LBB0_116:
	s_ashr_i32 s7, s6, 31
	s_lshl_b64 s[6:7], s[6:7], 11
	v_lshl_add_u64 v[68:69], v[66:67], 0, s[6:7]
	s_waitcnt vmcnt(7)
	v_cvt_pk_f16_f32 v36, v36, v37
	v_cvt_pk_f16_f32 v37, v38, v39
	s_waitcnt vmcnt(6)
	v_cvt_pk_f16_f32 v16, v16, v17
	v_cvt_pk_f16_f32 v17, v18, v19
	s_waitcnt vmcnt(3)
	v_cvt_pk_f16_f32 v8, v8, v9
	v_cvt_pk_f16_f32 v9, v10, v11
	s_waitcnt vmcnt(2)
	v_cvt_pk_f16_f32 v0, v0, v1
	v_cvt_pk_f16_f32 v1, v2, v3
	global_store_dwordx2 v[68:69], v[36:37], off sc1
	v_cvt_pk_f16_f32 v36, v52, v53
	v_cvt_pk_f16_f32 v37, v54, v55
	global_store_dwordx2 v[68:69], v[16:17], off offset:512 sc1
	v_cvt_pk_f16_f32 v16, v20, v21
	v_cvt_pk_f16_f32 v17, v22, v23
	global_store_dwordx2 v[68:69], v[8:9], off offset:1024 sc1
	s_waitcnt vmcnt(4)
	v_cvt_pk_f16_f32 v8, v12, v13
	v_cvt_pk_f16_f32 v9, v14, v15
	global_store_dwordx2 v[68:69], v[0:1], off offset:1536 sc1
	s_waitcnt vmcnt(4)
	v_cvt_pk_f16_f32 v0, v4, v5
	v_cvt_pk_f16_f32 v1, v6, v7
	global_store_dwordx2 v[68:69], v[36:37], off offset:2048 sc1
	global_store_dwordx2 v[68:69], v[16:17], off offset:2560 sc1
	global_store_dwordx2 v[68:69], v[8:9], off offset:3072 sc1
	global_store_dwordx2 v[68:69], v[0:1], off offset:3584 sc1
	v_mov_b64_e32 v[0:1], v[40:41]
	v_mov_b64_e32 v[8:9], v[32:33]
	v_mov_b64_e32 v[16:17], v[28:29]
	v_mov_b64_e32 v[38:39], v[26:27]
	v_mov_b64_e32 v[4:5], v[56:57]
	v_mov_b64_e32 v[12:13], v[60:61]
	v_mov_b64_e32 v[20:21], v[44:45]
	v_mov_b64_e32 v[54:55], v[50:51]
	s_add_i32 s1, s1, 2
	s_andn2_b64 vcc, exec, s[4:5]
	v_mov_b64_e32 v[2:3], v[42:43]
	v_mov_b64_e32 v[10:11], v[34:35]
	v_mov_b64_e32 v[18:19], v[30:31]
	v_mov_b64_e32 v[36:37], v[24:25]
	v_mov_b64_e32 v[6:7], v[58:59]
	v_mov_b64_e32 v[14:15], v[62:63]
	v_mov_b64_e32 v[22:23], v[46:47]
	v_mov_b64_e32 v[52:53], v[48:49]
	s_cbranch_vccz .LBB0_119

.LBB0_121:
	v_ashrrev_i32_e32 v54, 4, v52
	v_ashrrev_i32_e32 v55, 31, v54
	v_lshl_add_u64 v[54:55], v[54:55], 2, s[8:9]
	global_load_dword v80, v[54:55], off nt
	v_mov_b32_e32 v0, v48
	v_mov_b64_e32 v[74:75], v[0:1]
	v_mov_b64_e32 v[54:55], v[32:33]
	v_mov_b64_e32 v[58:59], v[42:43]
	v_mov_b64_e32 v[56:57], v[40:41]
	v_mov_b64_e32 v[62:63], v[46:47]
	v_mov_b64_e32 v[60:61], v[44:45]
	v_mov_b64_e32 v[66:67], v[50:51]
	v_mov_b64_e32 v[64:65], v[48:49]
	v_mov_b64_e32 v[68:69], v[2:3]
	v_mov_b64_e32 v[72:73], v[4:5]
	v_mov_b32_e32 v8, v6
	v_mov_b64_e32 v[70:71], v[6:7]
	v_mov_b64_e32 v[76:77], v[8:9]
	v_add_u32_e32 v52, s18, v52
	v_ashrrev_i32_e32 v11, 31, v10
	v_cmp_lt_i32_e32 vcc, s20, v52
	v_lshl_add_u64 v[78:79], v[10:11], 2, s[6:7]
	v_add_u32_e32 v10, s19, v10
	s_or_b64 s[0:1], vcc, s[0:1]
	s_waitcnt vmcnt(0)
	v_cvt_f32_i32_e32 v0, v80
	v_mul_f32_e32 v0, v53, v0
	v_cvt_f64_f32_e32 v[80:81], v0
	v_mul_f64 v[82:83], v[80:81], s[10:11]
	v_rndne_f64_e32 v[82:83], v[82:83]
	v_fma_f64 v[80:81], v[80:81], s[10:11], -v[82:83]
	v_mul_f64 v[80:81], v[80:81], s[12:13]
	v_mul_f64 v[82:83], v[80:81], -v[80:81]
	v_fma_f64 v[86:87], s[16:17], v[82:83], v[14:15]
	v_fma_f64 v[84:85], s[14:15], v[82:83], v[12:13]
	v_fma_f64 v[86:87], v[82:83], v[86:87], v[18:19]
	v_fma_f64 v[84:85], v[82:83], v[84:85], v[16:17]
	v_fma_f64 v[86:87], v[82:83], v[86:87], v[22:23]
	v_fma_f64 v[84:85], v[82:83], v[84:85], v[20:21]
	v_fma_f64 v[86:87], v[82:83], v[86:87], v[26:27]
	v_fma_f64 v[84:85], v[82:83], v[84:85], v[24:25]
	v_fma_f64 v[86:87], v[82:83], v[86:87], v[30:31]
	v_fma_f64 v[84:85], v[82:83], v[84:85], v[28:29]
	v_fma_f64 v[86:87], v[82:83], v[86:87], v[36:37]
	v_fma_f64 v[84:85], v[82:83], v[84:85], v[34:35]
	v_fmac_f64_e32 v[54:55], v[82:83], v[86:87]
	v_fma_f64 v[84:85], v[82:83], v[84:85], v[38:39]
	v_fmac_f64_e32 v[58:59], v[82:83], v[54:55]
	v_fmac_f64_e32 v[56:57], v[82:83], v[84:85]
	v_fmac_f64_e32 v[62:63], v[82:83], v[58:59]
	v_fmac_f64_e32 v[60:61], v[82:83], v[56:57]
	v_fmac_f64_e32 v[66:67], v[82:83], v[62:63]
	v_fmac_f64_e32 v[64:65], v[82:83], v[60:61]
	v_fmac_f64_e32 v[74:75], v[82:83], v[66:67]
	v_fmac_f64_e32 v[68:69], v[82:83], v[64:65]
	v_fmac_f64_e32 v[72:73], v[82:83], v[74:75]
	v_fmac_f64_e32 v[70:71], v[82:83], v[68:69]
	v_fmac_f64_e32 v[76:77], v[82:83], v[72:73]
	v_fma_f64 v[54:55], v[82:83], v[70:71], 0.5
	v_fma_f64 v[56:57], v[82:83], v[76:77], 1.0
	v_fma_f64 v[54:55], v[82:83], v[54:55], 1.0
	v_mul_f64 v[56:57], v[80:81], v[56:57]
	v_cvt_f32_f64_e32 v54, v[54:55]
	v_cvt_f32_f64_e32 v55, v[56:57]
	global_store_dwordx2 v[78:79], v[54:55], off sc1
	s_andn2_b64 exec, exec, s[0:1]
	s_cbranch_execnz .LBB0_121

.LBB0_125:
	v_lshl_add_u64 v[8:9], s[22:23], 0, v[2:3]
	global_load_dword v5, v[8:9], off nt
	v_add_u32_e32 v0, s4, v0
	v_cmp_lt_i32_e32 vcc, s16, v0
	s_or_b64 s[8:9], vcc, s[8:9]
	v_lshl_add_u64 v[8:9], s[2:3], 0, v[2:3]
	v_lshl_add_u64 v[2:3], v[2:3], 0, s[6:7]
	s_waitcnt vmcnt(0)
	v_mul_f32_e32 v7, 0xbfb8aa3b, v5
	v_fma_f32 v10, v5, s5, -v7
	v_rndne_f32_e32 v11, v7
	v_fmac_f32_e32 v10, 0xb2a5705f, v5
	v_sub_f32_e32 v7, v7, v11
	v_add_f32_e32 v7, v7, v10
	v_cvt_i32_f32_e32 v11, v11
	v_exp_f32_e32 v7, v7
	v_cmp_nlt_f32_e32 vcc, s10, v5
	v_ldexp_f32 v7, v7, v11
	s_nop 0
	v_cndmask_b32_e32 v7, 0, v7, vcc
	v_cmp_ngt_f32_e32 vcc, s11, v5
	s_nop 1
	v_cndmask_b32_e32 v7, v1, v7, vcc
	v_add_f32_e32 v5, 1.0, v7
	v_add_f32_e32 v12, -1.0, v5
	v_frexp_mant_f32_e32 v13, v5
	v_cvt_f64_f32_e32 v[10:11], v5
	v_sub_f32_e32 v14, v12, v5
	v_frexp_exp_i32_f64_e32 v10, v[10:11]
	v_cmp_gt_f32_e32 vcc, s13, v13
	v_sub_f32_e32 v12, v7, v12
	v_add_f32_e32 v11, 1.0, v14
	v_subbrev_co_u32_e32 v10, vcc, 0, v10, vcc
	v_add_f32_e32 v11, v12, v11
	v_sub_u32_e32 v12, 0, v10
	v_ldexp_f32 v5, v5, v12
	v_ldexp_f32 v11, v11, v12
	v_add_f32_e32 v12, -1.0, v5
	v_add_f32_e32 v14, 1.0, v5
	v_add_f32_e32 v13, 1.0, v12
	v_add_f32_e32 v15, -1.0, v14
	v_sub_f32_e32 v13, v5, v13
	v_sub_f32_e32 v5, v5, v15
	v_add_f32_e32 v5, v11, v5
	v_add_f32_e32 v15, v11, v13
	v_add_f32_e32 v11, v14, v5
	v_rcp_f32_e32 v18, v11
	v_add_f32_e32 v13, v12, v15
	v_sub_f32_e32 v14, v14, v11
	v_add_f32_e32 v5, v5, v14
	v_mul_f32_e32 v20, v13, v18
	v_mul_f32_e32 v14, v11, v20
	v_fma_f32 v16, v20, v11, -v14
	v_sub_f32_e32 v12, v12, v13
	v_fmac_f32_e32 v16, v20, v5
	v_add_f32_e32 v19, v15, v12
	v_add_f32_e32 v12, v14, v16
	v_sub_f32_e32 v15, v13, v12
	v_mov_b32_e32 v17, v12
	v_pk_add_f32 v[12:13], v[12:13], v[14:15] neg_lo:[0,1] neg_hi:[0,1]
	v_cvt_f32_i32_e32 v10, v10
	v_pk_add_f32 v[12:13], v[12:13], v[16:17] neg_lo:[0,1] neg_hi:[0,1]
	v_cmp_neq_f32_e32 vcc, s12, v7
	v_add_f32_e32 v13, v19, v13
	v_add_f32_e32 v12, v12, v13
	v_add_f32_e32 v13, v15, v12
	v_mul_f32_e32 v17, v18, v13
	v_mul_f32_e32 v14, v11, v17
	v_fma_f32 v16, v17, v11, -v14
	v_sub_f32_e32 v15, v15, v13
	v_fmac_f32_e32 v16, v17, v5
	v_add_f32_e32 v19, v12, v15
	v_add_f32_e32 v21, v20, v17
	v_add_f32_e32 v12, v14, v16
	v_sub_f32_e32 v11, v21, v20
	v_sub_f32_e32 v15, v13, v12
	v_sub_f32_e32 v5, v17, v11
	v_mov_b32_e32 v17, v12
	v_pk_add_f32 v[12:13], v[12:13], v[14:15] neg_lo:[0,1] neg_hi:[0,1]
	s_nop 0
	v_pk_add_f32 v[12:13], v[12:13], v[16:17] neg_lo:[0,1] neg_hi:[0,1]
	s_nop 0
	v_add_f32_e32 v11, v19, v13
	v_add_f32_e32 v11, v12, v11
	v_add_f32_e32 v11, v15, v11
	v_mul_f32_e32 v11, v18, v11
	v_add_f32_e32 v5, v5, v11
	v_add_f32_e32 v11, v21, v5
	v_mul_f32_e32 v12, v11, v11
	v_sub_f32_e32 v14, v11, v21
	v_fmamk_f32 v15, v12, 0x3e9b6dac, v6
	v_ldexp_f32 v13, v11, 1
	v_sub_f32_e32 v14, v5, v14
	v_mul_f32_e32 v11, v11, v12
	v_fmaak_f32 v5, v12, v15, 0x3f2aaada
	v_ldexp_f32 v17, v14, 1
	v_pk_mul_f32 v[14:15], v[10:11], v[4:5]
	s_nop 0
	v_fma_f32 v12, v10, s14, -v14
	v_fmac_f32_e32 v12, 0xb102e308, v10
	v_pk_add_f32 v[10:11], v[14:15], v[12:13]
	v_mov_b32_e32 v16, v14
	v_sub_f32_e32 v5, v11, v13
	v_sub_f32_e32 v5, v15, v5
	v_add_f32_e32 v17, v17, v5
	v_pk_add_f32 v[18:19], v[10:11], v[14:15] neg_lo:[0,1] neg_hi:[0,1]
	v_pk_add_f32 v[14:15], v[10:11], v[16:17]
	v_mov_b32_e32 v13, v10
	v_mov_b32_e32 v19, v15
	v_pk_add_f32 v[22:23], v[12:13], v[18:19] neg_lo:[0,1] neg_hi:[0,1]
	v_pk_add_f32 v[12:13], v[12:13], v[18:19]
	v_mov_b32_e32 v21, v10
	v_pk_add_f32 v[18:19], v[12:13], v[10:11] op_sel:[1,0] op_sel_hi:[0,1] neg_lo:[0,1] neg_hi:[0,1]
	v_mov_b32_e32 v20, v17
	v_mov_b32_e32 v16, v15
	v_mov_b32_e32 v17, v13
	v_pk_mov_b32 v[10:11], v[10:11], v[18:19] op_sel:[1,0]
	v_pk_add_f32 v[14:15], v[14:15], v[18:19] op_sel_hi:[1,0] neg_lo:[0,1] neg_hi:[0,1]
	v_pk_add_f32 v[10:11], v[16:17], v[10:11] neg_lo:[0,1] neg_hi:[0,1]
	v_mov_b32_e32 v14, v22
	v_pk_add_f32 v[10:11], v[20:21], v[10:11] neg_lo:[0,1] neg_hi:[0,1]
	v_mov_b32_e32 v23, v13
	v_pk_add_f32 v[14:15], v[14:15], v[10:11]
	s_nop 0
	v_pk_add_f32 v[16:17], v[14:15], v[14:15] op_sel:[0,1] op_sel_hi:[1,0]
	s_nop 0
	v_pk_add_f32 v[12:13], v[12:13], v[16:17] op_sel:[1,0] op_sel_hi:[0,1]
	v_mov_b32_e32 v15, v12
	v_mov_b32_e32 v11, v16
	v_pk_add_f32 v[16:17], v[14:15], v[22:23] neg_lo:[0,1] neg_hi:[0,1]
	s_nop 0
	v_sub_f32_e32 v5, v14, v16
	v_pk_add_f32 v[10:11], v[10:11], v[16:17] neg_lo:[0,1] neg_hi:[0,1]
	v_sub_f32_e32 v5, v22, v5
	v_add_f32_e32 v5, v10, v5
	v_add_f32_e32 v5, v5, v11
	v_add_f32_e32 v5, v12, v5
	v_cndmask_b32_e32 v5, v1, v5, vcc
	v_cmp_lt_f32_e64 vcc, |v7|, s15
	s_nop 1
	v_cndmask_b32_e32 v5, v5, v7, vcc
	v_mul_f32_e32 v5, 0xc138aa3b, v5
	global_store_dword v[8:9], v5, off sc1
	s_andn2_b64 exec, exec, s[8:9]
	s_cbranch_execnz .LBB0_125

.LBB0_161:
	s_andn2_saveexec_b64 s[4:5], s[4:5]
	s_cbranch_execz .LBB0_181
	s_mov_b64 s[4:5], exec
	s_waitcnt vmcnt(0) lgkmcnt(0)
	s_waitcnt vmcnt(0)
	v_mbcnt_lo_u32_b32 v1, s4, 0
	v_mbcnt_hi_u32_b32 v1, s5, v1
	v_cmp_eq_u32_e32 vcc, 0, v1
	s_and_saveexec_b64 s[6:7], vcc
	s_cbranch_execz .LBB0_164
	s_bcnt1_i32_b64 s4, s[4:5]
	v_mov_b32_e32 v2, 0x3000
	v_mov_b32_e32 v3, s4
	global_atomic_add v2, v2, v3, s[92:93] offset:1024 sc0
